# static s_setprio 1 for waves 4-7 kept through the whole attention phase (A, C, B)
# baseline (speedup 1.0000x reference)
; #define GSYNC() xcd_barrier(xbar)
; __device__ __forceinline__ void xcd_barrier(const XcdBarrier& b) {
;     asm volatile("s_waitcnt vmcnt(0)" ::: "memory");
;     __syncthreads();
;     if (threadIdx.x == 0) {
;         unsigned* bar = b.bar;
;         __builtin_amdgcn_s_waitcnt(0);
;         unsigned nloc = b.st[0], nx = b.st[1];
;         if (nloc == 0u) { xcd_barrier_complete(bar, b.x, nloc, nx); b.st[0] = nloc; b.st[1] = nx; }
; __global__ void __launch_bounds__(NWAVES * 64, 2) fwd_megakernel(Params P) {
;     ...
;         GSYNC();
.LBB0_546:
	s_setprio 0
	s_waitcnt vmcnt(0)
	s_barrier
	s_mov_b64 s[0:1], exec
	v_readlane_b32 s4, v252, 0
	v_readlane_b32 s5, v252, 1
	s_and_b64 s[4:5], s[0:1], s[4:5]
	s_mov_b64 exec, s[4:5]
	s_cbranch_execz .LBB0_598
	v_readlane_b32 s4, v254, 44
	s_waitcnt vmcnt(0) expcnt(0) lgkmcnt(0)
	s_nop 0
	v_mov_b32_e32 v0, s4
	ds_read_b32 v2, v0
	v_readlane_b32 s4, v254, 45
	s_waitcnt lgkmcnt(0)
	v_cmp_ne_u32_e32 vcc, 0, v2
	v_mov_b32_e32 v0, s4
	ds_read_b32 v0, v0
	s_cbranch_vccnz .LBB0_560
	s_mov_b32 s12, 1
	s_branch .LBB0_550
